# code placement: scan chunk loop, attention item loop and phase-2 K-loop pinned with .p2align 6 + nops (phases 8 / 28 / 32 bytes mod 64)
# speedup vs baseline: 1.0275x; 1.0058x over previous
; #define GLOAD(kt) do { const int ko = (kt) * BK; \
;     ra0 = *(const uint4*)(gA + ko); ra1 = *(const uint4*)(gA + sA + ko); ra2 = *(const uint4*)(gA + 2 * sA + ko); ra3 = *(const uint4*)(gA + 3 * sA + ko); \
;     rb0 = *(const uint4*)(gB + ko); rb1 = *(const uint4*)(gB + sB + ko); rb2 = *(const uint4*)(gB + 2 * sB + ko); rb3 = *(const uint4*)(gB + 3 * sB + ko); } while (0)
; #define LSTORE(st) do { \
;     *(uint4*)(lA + (st) * ASZ) = ra0; *(uint4*)(lA + (st) * ASZ + 64 * LDT) = ra1; *(uint4*)(lA + (st) * ASZ + 128 * LDT) = ra2; *(uint4*)(lA + (st) * ASZ + 192 * LDT) = ra3; \
;     *(uint4*)(lB + (st) * BSZ) = rb0; *(uint4*)(lB + (st) * BSZ + 64 * LDT) = rb1; *(uint4*)(lB + (st) * BSZ + 128 * LDT) = rb2; *(uint4*)(lB + (st) * BSZ + 192 * LDT) = rb3; } while (0)
; template <class Epi>
; DI void gemm_tile(const GemmDesc g, int m0, int n0, unsigned char* lds, Epi& epi) {
;     ...
;       for (int e = 0; e < 16; ++e) acc[i][j][e] = 0.f;
;   uint4 ra0, ra1, ra2, ra3, rb0, rb1, rb2, rb3;
;   const int nk = g.K / BK;
;   const bf16_t* gA = g.A + (size_t)(m0 + (tid >> 3)) * g.lda + (tid & 7) * 8;
;   const bf16_t* gB = g.Bt + (size_t)(n0 + (tid >> 3)) * g.ldb + (tid & 7) * 8;
;   const size_t sA = (size_t)64 * g.lda, sB = (size_t)64 * g.ldb;
;   bf16_t* lA = As + (tid >> 3) * LDT + (tid & 7) * 8;
;   bf16_t* lB = Bs + (tid >> 3) * LDT + (tid & 7) * 8;
;   const bf16_t* fA = As + (wm * 128 + (lane & 31)) * LDT + (lane >> 5) * 8;
;   const bf16_t* fB = Bs + (wn * 64 + (lane & 31)) * LDT + (lane >> 5) * 8;
;     ...
;   __syncthreads();
;   GLOAD(0);
;   LSTORE(0);
;   __syncthreads();
.Lg2_swz_done:
	v_mov_b32_e32 v174, v208
	s_lshl_b32 s8, s1, 8
	v_ashrrev_i32_e32 v43, 3, v174
	v_add_u32_e32 v0, s8, v43
	v_ashrrev_i32_e32 v1, 31, v0
	v_lshlrev_b64 v[38:39], 11, v[0:1]
	v_lshlrev_b32_e32 v2, 4, v174
	v_lshl_add_u64 v[0:1], s[52:53], 0, v[38:39]
	v_and_b32_e32 v160, 0x70, v2
	s_mov_b32 s1, s7
	v_lshl_add_u64 v[0:1], v[0:1], 0, v[160:161]
	s_lshl_b32 s1, s1, 8
	v_add_co_u32_e32 v4, vcc, s3, v0
	v_add_u32_e32 v2, s1, v43
	s_nop 0
	v_addc_co_u32_e32 v5, vcc, 0, v1, vcc
	v_ashrrev_i32_e32 v3, 31, v2
	v_add_co_u32_e32 v10, vcc, s89, v0
	v_lshlrev_b64 v[40:41], 11, v[2:3]
	s_nop 0
	v_addc_co_u32_e32 v11, vcc, 0, v1, vcc
	v_lshl_add_u64 v[2:3], s[54:55], 0, v[40:41]
	s_barrier
	global_load_dwordx4 v[6:9], v[4:5], off
	s_nop 0
	global_load_dwordx4 v[10:13], v[10:11], off
	v_add_co_u32_e32 v4, vcc, s90, v0
	v_lshl_add_u64 v[2:3], v[2:3], 0, v[160:161]
	s_nop 0
	v_addc_co_u32_e32 v5, vcc, 0, v1, vcc
	global_load_dwordx4 v[14:17], v[0:1], off
	global_load_dwordx4 v[18:21], v[2:3], off
	v_add_co_u32_e32 v0, vcc, s3, v2
	v_and_b32_e32 v175, 31, v174
	s_nop 0
	v_addc_co_u32_e32 v1, vcc, 0, v3, vcc
	global_load_dwordx4 v[22:25], v[4:5], off
	global_load_dwordx4 v[26:29], v[0:1], off
	v_add_co_u32_e32 v0, vcc, s89, v2
	v_ashrrev_i32_e32 v5, 1, v174
	s_nop 0
	v_addc_co_u32_e32 v1, vcc, 0, v3, vcc
	v_add_co_u32_e32 v2, vcc, s90, v2
	v_bfe_u32 v176, v174, 5, 1
	s_nop 0
	v_addc_co_u32_e32 v3, vcc, 0, v3, vcc
	global_load_dwordx4 v[30:33], v[0:1], off
	global_load_dwordx4 v[34:37], v[2:3], off
	v_and_b32_e32 v44, 0xdf, v174
	v_and_b32_e32 v177, 0xffffff80, v5
	s_mov_b32 s6, 0x12000
	v_and_b32_e32 v45, 7, v174
	v_lshlrev_b32_e32 v42, 4, v176
	v_mul_u32_u24_e32 v5, 0x90, v44
	v_mad_u64_u32 v[162:163], s[4:5], v43, s2, v[160:161]
	v_or_b32_e32 v43, v177, v175
	s_mov_b32 s9, 0
	v_mov_b32_e32 v0, v161
	v_mov_b32_e32 v1, v161
	v_mov_b32_e32 v2, v161
	v_mov_b32_e32 v3, v161
	v_mov_b32_e32 v4, v161
	v_add3_u32 v163, v5, v42, s6
	v_add_u32_e32 v178, 0x12000, v162
	v_mad_u64_u32 v[164:165], s[4:5], v43, s2, v[42:43]
	v_lshl_add_u64 v[166:167], s[94:95], 0, v[38:39]
	v_lshl_add_u64 v[168:169], s[94:95], 0, v[40:41]
	v_lshlrev_b32_e32 v160, 4, v45
	v_mov_b32_e32 v5, v161
	v_mov_b32_e32 v38, v161
	v_mov_b32_e32 v39, v161
	v_mov_b32_e32 v40, v161
	v_mov_b32_e32 v41, v161
	v_mov_b32_e32 v42, v161
	v_mov_b32_e32 v43, v161
	v_mov_b32_e32 v44, v161
	v_mov_b32_e32 v45, v161
	v_mov_b32_e32 v46, v161
	v_mov_b32_e32 v47, v161
	v_mov_b32_e32 v48, v161
	v_mov_b32_e32 v49, v161
	v_mov_b32_e32 v50, v161
	v_mov_b32_e32 v51, v161
	v_mov_b32_e32 v52, v161
	v_mov_b32_e32 v53, v161
	v_mov_b32_e32 v54, v161
	v_mov_b32_e32 v55, v161
	v_mov_b32_e32 v56, v161
	v_mov_b32_e32 v57, v161
	s_waitcnt vmcnt(5)
	ds_write_b128 v162, v[14:17]
	ds_write_b128 v162, v[6:9] offset:9216
	ds_write_b128 v162, v[10:13] offset:18432
	s_waitcnt vmcnt(3)
	ds_write_b128 v162, v[22:25] offset:27648
	ds_write_b128 v178, v[18:21]
	s_waitcnt vmcnt(2)
	ds_write_b128 v178, v[26:29] offset:9216
	s_waitcnt vmcnt(1)
	ds_write_b128 v178, v[30:33] offset:18432
	s_waitcnt vmcnt(0)
	ds_write_b128 v178, v[34:37] offset:27648
	v_mov_b32_e32 v6, v161
	v_mov_b32_e32 v7, v161
	v_mov_b32_e32 v8, v161
	v_mov_b32_e32 v9, v161
	v_mov_b32_e32 v10, v161
	v_mov_b32_e32 v11, v161
	v_mov_b32_e32 v12, v161
	v_mov_b32_e32 v13, v161
	v_mov_b32_e32 v14, v161
	v_mov_b32_e32 v15, v161
	v_mov_b32_e32 v16, v161
	v_mov_b32_e32 v17, v161
	v_mov_b32_e32 v18, v161
	v_mov_b32_e32 v19, v161
	v_mov_b32_e32 v20, v161
	v_mov_b32_e32 v21, v161
	v_mov_b32_e32 v22, v161
	v_mov_b32_e32 v23, v161
	v_mov_b32_e32 v24, v161
	v_mov_b32_e32 v25, v161
	v_mov_b32_e32 v26, v161
	v_mov_b32_e32 v27, v161
	v_mov_b32_e32 v28, v161
	v_mov_b32_e32 v29, v161
	v_mov_b32_e32 v30, v161
	v_mov_b32_e32 v31, v161
	v_mov_b32_e32 v32, v161
	v_mov_b32_e32 v33, v161
	v_mov_b32_e32 v34, v161
	v_mov_b32_e32 v35, v161
	v_mov_b32_e32 v36, v161
	v_mov_b32_e32 v37, v161
	v_mov_b32_e32 v58, v161
	v_mov_b32_e32 v59, v161
	v_mov_b32_e32 v60, v161
	v_mov_b32_e32 v61, v161
	v_mov_b32_e32 v62, v161
	v_mov_b32_e32 v63, v161
	v_mov_b32_e32 v64, v161
	v_mov_b32_e32 v65, v161
	v_mov_b32_e32 v66, v161
	v_mov_b32_e32 v67, v161
	v_mov_b32_e32 v68, v161
	v_mov_b32_e32 v69, v161
	v_mov_b32_e32 v70, v161
	v_mov_b32_e32 v71, v161
	v_mov_b32_e32 v72, v161
	v_mov_b32_e32 v73, v161
	v_mov_b32_e32 v74, v161
	v_mov_b32_e32 v75, v161
	v_mov_b32_e32 v76, v161
	v_mov_b32_e32 v77, v161
	v_mov_b32_e32 v78, v161
	v_mov_b32_e32 v79, v161
	v_mov_b32_e32 v80, v161
	v_mov_b32_e32 v81, v161
	v_mov_b32_e32 v82, v161
	v_mov_b32_e32 v83, v161
	v_mov_b32_e32 v84, v161
	v_mov_b32_e32 v85, v161
	v_mov_b32_e32 v86, v161
	v_mov_b32_e32 v87, v161
	v_mov_b32_e32 v88, v161
	v_mov_b32_e32 v89, v161
	v_mov_b32_e32 v90, v161
	v_mov_b32_e32 v91, v161
	v_mov_b32_e32 v92, v161
	v_mov_b32_e32 v93, v161
	v_mov_b32_e32 v94, v161
	v_mov_b32_e32 v95, v161
	v_mov_b32_e32 v96, v161
	v_mov_b32_e32 v97, v161
	v_mov_b32_e32 v98, v161
	v_mov_b32_e32 v99, v161
	v_mov_b32_e32 v100, v161
	v_mov_b32_e32 v101, v161
	v_mov_b32_e32 v102, v161
	v_mov_b32_e32 v103, v161
	v_mov_b32_e32 v104, v161
	v_mov_b32_e32 v105, v161
	v_mov_b32_e32 v106, v161
	v_mov_b32_e32 v107, v161
	v_mov_b32_e32 v108, v161
	v_mov_b32_e32 v109, v161
	v_mov_b32_e32 v110, v161
	v_mov_b32_e32 v111, v161
	v_mov_b32_e32 v112, v161
	v_mov_b32_e32 v113, v161
	v_mov_b32_e32 v114, v161
	v_mov_b32_e32 v115, v161
	v_mov_b32_e32 v116, v161
	v_mov_b32_e32 v117, v161
	v_mov_b32_e32 v118, v161
	v_mov_b32_e32 v119, v161
	v_mov_b32_e32 v120, v161
	v_mov_b32_e32 v121, v161
	v_mov_b32_e32 v122, v161
	v_mov_b32_e32 v123, v161
	v_mov_b32_e32 v124, v161
	v_mov_b32_e32 v125, v161
	v_mov_b32_e32 v126, v161
	v_mov_b32_e32 v127, v161
	s_waitcnt lgkmcnt(0)
	s_barrier
	s_branch .LBB0_193
	.p2align 6
	s_nop 0
	s_nop 0
	s_nop 0
	s_nop 0
	s_nop 0
	s_nop 0
	s_nop 0
	s_nop 0

; DI void scan_task(const Params& P, int sb, unsigned char* lds) {
;     ...
;     const int q = lane & 15, q4 = q * 4, rowl = w * 4 + (lane >> 4);
;     const bool o1 = (lane & 1) != 0, o2 = (lane & 2) != 0;
;     f2 S0 = {0.f, 0.f}, S1 = {0.f, 0.f};
;     __syncthreads();
;     for (int c = 0; c < NCH; ++c) {
.LBB0_1193:
	s_andn2_b64 vcc, exec, s[4:5]
	s_cbranch_vccnz .LBB0_1235
	s_bitcmp0_b32 s76, 2
	s_cbranch_scc1 .LBB0_1235
	v_readfirstlane_b32 s1, v208
	s_cmpk_lt_u32 s1, 0x100
	s_mov_b64 s[4:5], -1
	s_waitcnt vmcnt(63) expcnt(7) lgkmcnt(15)
	s_barrier
	s_cbranch_scc0 .LBB0_1201
	s_setprio 3
	v_lshlrev_b32_e32 v0, 2, v208
	v_and_b32_e32 v68, 60, v0
	v_and_b32_e32 v0, 1, v208
	s_and_b32 s3, s1, 0xc0
	v_cmp_eq_u32_e32 vcc, 0, v0
	v_and_b32_e32 v0, 2, v208
	v_and_b32_e32 v1, 15, v208
	v_mov_b32_e32 v2, 0x1080
	v_cmp_eq_u32_e64 s[4:5], 0, v0
	v_bfe_u32 v0, v208, 2, 2
	v_lshl_add_u32 v69, v1, 4, v2
	v_and_or_b32 v1, v208, 48, s3
	v_lshrrev_b32_e32 v1, 2, v1
	v_lshlrev_b32_e32 v0, 6, v0
	s_mov_b32 s3, 0x16000
	v_or3_b32 v70, v1, v0, s3
	s_lshl_b32 s1, s1, 3
	v_lshlrev_b32_e32 v0, 3, v208
	v_mov_b32_e32 v64, 0
	s_and_b32 s1, s1, 0x600
	v_and_b32_e32 v0, 0x180, v0
	v_mov_b32_e32 v65, v64
	s_mov_b32 s0, 0
	v_or_b32_e32 v71, s1, v0
	s_mov_b64 s[6:7], 0
	s_mov_b32 s1, 0xb000
	v_mov_b64_e32 v[66:67], v[64:65]
	s_barrier
	.p2align 6
	s_nop 0
	s_nop 0

; #define TLOAD(kt) do { const int key0 = (kt) * 64; \
;     rk = *(const uint4*)(KN + (size_t)(key0 + (tid >> 3)) * 64 + (tid & 7) * 8); \
;     if (tid < 256) rr = *(const uint4*)(KR + (size_t)(key0 + (tid >> 2)) * 32 + (tid & 3) * 8); \
;     rv = *(const uint4*)(VT + (size_t)(tid >> 3) * LK + key0 + (tid & 7) * 8); } while (0)
; DI void attn_item(const Params& P, int item, unsigned char* lds) {
;     ...
;   for (int kt = 0; kt < NKT; ++kt) {
;     { const int k1 = (kt + 1 < NKT) ? kt + 1 : NKT - 1; TLOAD(k1); }
;     const bf16_t* Ks = Kl + (kt & 1) * KB; const bf16_t* Vs = Vl + (kt & 1) * VB;
.LBB0_1237:
	s_and_b64 vcc, exec, s[4:5]
	s_cbranch_vccnz .LBB0_1267
	.p2align 6
	s_nop 0
	s_nop 0
	s_nop 0
	s_nop 0
	s_nop 0
	s_nop 0
	s_nop 0
